# attention-A static priority removed as well (no s_setprio anywhere), on top of the SGPR-base K/V loads
# speedup vs baseline: 1.0007x; 1.0006x over previous
; #define FLAS __attribute__((address_space(3)))
; __device__ __forceinline__ void attn_unit_a(FLAS unsigned char* lds, const Unit u) {
;     ...
;     const f32x16 z16 = {0.f,0.f,0.f,0.f,0.f,0.f,0.f,0.f,0.f,0.f,0.f,0.f,0.f,0.f,0.f,0.f};
;     f32x16 o[NDB];
; #pragma unroll
;     for (int i = 0; i < NDB; ++i) o[i] = z16;
;     float mrun = 0.f, lsum = 0.f, fpend = 1.f; bool first = true, pend = false;
;     ...
;     f32x16 pa0, pa1, pb0, pb1; float cbC = 0.f;
;     { bool zi; FA_BIAS(0, pa0, pa1, cbC, zi); if (zi) { pa0 = z16; pa1 = z16; }
;       const FLAS unsigned char* kb = lds + LA_K;
; #pragma unroll
;       for (int d0 = 0; d0 < 4; ++d0) { const int ko = (2 * d0 + hi) * 1024 + ((r32 ^ (2 * d0 + hi)) * 16); const bf16x8 a0 = *(const FLAS bf16x8*)(kb + ko), a1 = *(const FLAS bf16x8*)(kb + ko + 512);
;           pa0 = __builtin_amdgcn_mfma_f32_32x32x16_bf16(a0, qr[d0], pa0, 0, 0, 0); pa1 = __builtin_amdgcn_mfma_f32_32x32x16_bf16(a1, qr[d0], pa1, 0, 0, 0); } }
;     u32x4 pwa[4] = {{0u,0u,0u,0u},{0u,0u,0u,0u},{0u,0u,0u,0u},{0u,0u,0u,0u}}, pwb[4] = {{0u,0u,0u,0u},{0u,0u,0u,0u},{0u,0u,0u,0u},{0u,0u,0u,0u}};
.LBB0_432:
	v_xor_b32_e32 v1, v243, v5
	v_lshlrev_b32_e32 v1, 4, v1
	v_lshl_add_u32 v4, v243, 10, 0
	v_add_u32_e32 v247, v4, v1
	ds_read_b128 v[6:9], v247
	ds_read_b128 v[10:13], v247 offset:512
	v_or_b32_e32 v1, 2, v243
	v_bitop3_b32 v4, v243, v5, 2 bitop3:0x36
	v_lshlrev_b32_e32 v4, 4, v4
	v_lshl_add_u32 v1, v1, 10, 0
	v_add_u32_e32 v248, v1, v4
	s_waitcnt lgkmcnt(1)
	v_mfma_f32_32x32x16_bf16 v[128:143], v[6:9], v[160:163], v[128:143]
	ds_read_b128 v[6:9], v248
	v_or_b32_e32 v1, 4, v243
	v_bitop3_b32 v4, v243, v5, 4 bitop3:0x36
	v_lshlrev_b32_e32 v4, 4, v4
	v_lshl_add_u32 v1, v1, 10, 0
	v_add_u32_e32 v249, v1, v4
	s_lshr_b32 s0, s43, 8
	s_waitcnt lgkmcnt(1)
	v_mfma_f32_32x32x16_bf16 v[144:159], v[10:13], v[160:163], v[144:159]
	ds_read_b128 v[10:13], v248 offset:512
	s_lshl_b32 s15, s41, 1
	s_and_b32 s18, s40, 15
	s_and_b32 s0, s0, 1
	s_lshl_b32 s26, s42, 7
	s_bfe_u32 s1, s41, 0x2000d
	s_and_b32 s15, s15, 0xc000
	s_waitcnt lgkmcnt(1)
	v_mfma_f32_32x32x16_bf16 v[128:143], v[6:9], v[164:167], v[128:143]
	ds_read_b128 v[6:9], v249
	s_lshl_b32 s18, s18, 8
	s_lshl_b32 s20, s0, 7
	s_add_i32 s0, 0, 0x16000
	v_add_u32_e32 v240, s0, v224
	s_add_u32 s0, s70, s15
	s_mul_i32 s19, s1, 0x1800000
	s_waitcnt lgkmcnt(1)
	v_mfma_f32_32x32x16_bf16 v[144:159], v[10:13], v[164:167], v[144:159]
	ds_read_b128 v[10:13], v249 offset:512
	s_addc_u32 s1, s71, 0
	v_or_b32_e32 v1, 6, v243
	v_bitop3_b32 v4, v243, v5, 6 bitop3:0x36
	s_add_u32 s0, s0, s12
	v_lshlrev_b32_e32 v4, 4, v4
	v_lshl_add_u32 v1, v1, 10, 0
	s_waitcnt lgkmcnt(1)
	v_mfma_f32_32x32x16_bf16 v[128:143], v[6:9], v[168:171], v[128:143]
	s_addc_u32 s1, s1, 0
	v_add_u32_e32 v250, v1, v4
	v_lshl_add_u64 v[228:229], s[0:1], 0, v[2:3]
	s_lshl_b32 s0, s5, 8
	ds_read_b128 v[6:9], v250
	ds_read_b128 v[14:17], v250 offset:512
	s_and_b32 s0, s0, 0xfffff000
	s_or_b32 s0, s0, s18
	s_waitcnt lgkmcnt(2)
	v_mfma_f32_32x32x16_bf16 v[144:159], v[10:13], v[168:171], v[144:159]
	s_add_i32 s0, s0, s14
	s_sub_i32 s48, 64, s0
	v_add_lshl_u32 v1, s0, v5, 2
	s_add_u32 s0, s70, s20
	s_addc_u32 s1, s71, 0
	s_add_u32 s0, s0, s4
	s_addc_u32 s1, s1, 0
	s_waitcnt lgkmcnt(1)
	v_mfma_f32_32x32x16_bf16 v[128:143], v[6:9], v[172:175], v[128:143]
	s_add_u32 s0, s0, s19
	s_addc_u32 s1, s1, 0
	v_sub_u32_e32 v1, v224, v1
	v_mov_b64_e32 v[2:3], s[0:1]
	v_mul_u32_u24_e32 v246, 0x90, v5
	v_add_u32_e32 v210, 0, v1
	v_mad_i64_i32 v[230:231], s[0:1], v0, s65, v[2:3]
	s_waitcnt lgkmcnt(0)
	v_mfma_f32_32x32x16_bf16 v[144:159], v[14:17], v[172:175], v[144:159]
	v_mov_b32_e32 v14, v209
	v_mov_b32_e32 v15, v209
	v_mov_b32_e32 v0, v209
	v_mov_b32_e32 v1, v209
	v_mov_b32_e32 v2, v209
	v_mov_b32_e32 v3, v209
	v_mov_b32_e32 v4, v209
	v_mov_b32_e32 v5, v209
	v_mov_b32_e32 v6, v209
	v_mov_b32_e32 v7, v209
	v_mov_b32_e32 v8, v209
	v_mov_b32_e32 v9, v209
	v_mov_b32_e32 v10, v209
	v_mov_b32_e32 v11, v209
	v_mov_b32_e32 v12, v209
	v_mov_b32_e32 v13, v209
	v_mov_b32_e32 v188, 0
	v_mov_b64_e32 v[30:31], v[14:15]
	v_mov_b64_e32 v[46:47], v[14:15]
	v_mov_b64_e32 v[62:63], v[14:15]
	v_ashrrev_i32_e32 v223, 31, v222
	v_add3_u32 v251, 0, v246, v224
	s_mov_b32 s49, 0
	s_mov_b64 s[24:25], -1
	v_mov_b32_e32 v211, 0
	v_mov_b32_e32 v226, 1.0
	v_mov_b64_e32 v[28:29], v[12:13]
	v_mov_b64_e32 v[26:27], v[10:11]
	v_mov_b64_e32 v[24:25], v[8:9]
	v_mov_b64_e32 v[22:23], v[6:7]
	v_mov_b64_e32 v[20:21], v[4:5]
	v_mov_b64_e32 v[18:19], v[2:3]
	v_mov_b64_e32 v[16:17], v[0:1]
	v_mov_b64_e32 v[44:45], v[12:13]
	v_mov_b64_e32 v[42:43], v[10:11]
	v_mov_b64_e32 v[40:41], v[8:9]
	v_mov_b64_e32 v[38:39], v[6:7]
	v_mov_b64_e32 v[36:37], v[4:5]
	v_mov_b64_e32 v[34:35], v[2:3]
	v_mov_b64_e32 v[32:33], v[0:1]
	v_mov_b64_e32 v[60:61], v[12:13]
	v_mov_b64_e32 v[58:59], v[10:11]
	v_mov_b64_e32 v[56:57], v[8:9]
	v_mov_b64_e32 v[54:55], v[6:7]
	v_mov_b64_e32 v[52:53], v[4:5]
	v_mov_b64_e32 v[50:51], v[2:3]
	v_mov_b64_e32 v[48:49], v[0:1]
	s_mov_b32 s19, 0
	v_mov_b32_e32 v212, 0
	v_mov_b32_e32 v189, v188
	v_mov_b32_e32 v190, v188
	v_mov_b32_e32 v191, v188
	v_mov_b32_e32 v192, v188
	v_mov_b32_e32 v193, v188
	v_mov_b32_e32 v194, v188
	v_mov_b32_e32 v195, v188
	v_mov_b32_e32 v196, v188
	v_mov_b32_e32 v197, v188
	v_mov_b32_e32 v198, v188
	v_mov_b32_e32 v199, v188
	v_mov_b32_e32 v104, v188
	v_mov_b32_e32 v105, v188
	v_mov_b32_e32 v106, v188
	v_mov_b32_e32 v107, v188
	v_readfirstlane_b32 s100, v236
	s_nop 3
	s_cmp_lt_u32 s100, 0x100
	s_cbranch_scc1 .Lprio_skip
; #define FLAS __attribute__((address_space(3)))
; #define FA_SB() __builtin_amdgcn_sched_barrier(0)
; __device__ __forceinline__ float fadd_s(float a, float b) { float r; asm("v_add_f32_e32 %0, %1, %2" : "=v"(r) : "v"(a), "v"(b)); return r; }
; #define FA_PVM(G) do { o[(G) & 3] = __builtin_amdgcn_mfma_f32_32x32x16_bf16(__builtin_bit_cast(bf16x8, vr[(G) % 3]), __builtin_bit_cast(bf16x8, PWC[(G) >> 2]), o[(G) & 3], 0, 0, 0); if ((G) + 3 < 16) vr[(G) % 3] = FA_VFRAG((G) + 3); } while (0)
; __device__ __forceinline__ void attn_unit_a(FLAS unsigned char* lds, const Unit u) {
;     ...
;         if (pend) {
; #pragma unroll
;             for (int d = 0; d < NDB; ++d) o[d] = o[d] * fpend;
;             pend = false; }
;         if (i + 2 < NT) { kreg = *(const u32x4*)(ksrc + (size_t)(u.t_lo + i + 2) * 64 * u.ldk);
; #pragma unroll
;             for (int j = 0; j < 2; ++j) vreg[j] = *(const u32x4*)(vsrc + (size_t)j * 64 * MTOK + (u.t_lo + i + 2) * 64); }
;         const int vsp = (i == 0) ? 0 : ((i - 1) & 3);
;         const FLAS unsigned char* vb_ = lds + LA_V + vsp * VBUF + r32 * VPITCH + hi * 16;
;         const FLAS unsigned char* kb = lds + LA_K + ((i + 1) & 1) * KBUF;
;     ...
;         u32x4 vr[3];
; #pragma unroll
;         for (int m = 0; m < 3; ++m) vr[m] = FA_VFRAG(m);
;         const float off = cbC - mrun;
;         FA_SB();
;         float ra, rb, rm;
;         FA_PVM(0); pC0[0] = fadd_s(pC0[0], off); pC1[0] = fadd_s(pC1[0], off); pC0[1] = fadd_s(pC0[1], off); pC1[1] = fadd_s(pC1[1], off); pC0[2] = fadd_s(pC0[2], off); pC1[2] = fadd_s(pC1[2], off); FA_SB();
.Lprio_skip:
	s_waitcnt lgkmcnt(0)
	v_readlane_b32 s100, v254, 47
	v_mov_b32_e32 v92, s13
	s_nop 3
	v_mov_b32_e32 v93, s100
	ds_read_b32 v92, v92
	ds_read_b32 v93, v93
	v_sub_f32_e32 v94, v204, v211
	v_add_f32_e32 v96, v128, v94
	v_add_f32_e32 v112, v144, v94
	v_add_f32_e32 v97, v129, v94
	v_add_f32_e32 v113, v145, v94
	v_add_f32_e32 v98, v130, v94
	v_add_f32_e32 v114, v146, v94
	v_add_f32_e32 v99, v131, v94
	v_add_f32_e32 v115, v147, v94
	v_add_f32_e32 v100, v132, v94
	v_add_f32_e32 v116, v148, v94
	v_add_f32_e32 v101, v133, v94
	v_add_f32_e32 v117, v149, v94
	v_add_f32_e32 v102, v134, v94
	v_add_f32_e32 v118, v150, v94
	v_add_f32_e32 v103, v135, v94
	v_add_f32_e32 v119, v151, v94
	v_add_f32_e32 v104, v136, v94
	v_add_f32_e32 v120, v152, v94
	v_add_f32_e32 v105, v137, v94
	v_add_f32_e32 v121, v153, v94
	v_add_f32_e32 v106, v138, v94
	v_add_f32_e32 v122, v154, v94
	v_add_f32_e32 v107, v139, v94
	v_add_f32_e32 v123, v155, v94
	v_add_f32_e32 v108, v140, v94
	v_add_f32_e32 v124, v156, v94
	v_add_f32_e32 v109, v141, v94
	v_add_f32_e32 v125, v157, v94
	v_add_f32_e32 v110, v142, v94
	v_add_f32_e32 v126, v158, v94
	v_add_f32_e32 v111, v143, v94
	v_add_f32_e32 v127, v159, v94
	v_mov_b32_e32 v144, 0x7fc00000
	v_mov_b32_e32 v145, 0x7fc00000
	v_mov_b32_e32 v146, 0x7fc00000
	v_mov_b32_e32 v147, 0x7fc00000
	v_mov_b32_e32 v148, 0x7fc00000
	v_mov_b32_e32 v149, 0x7fc00000
	v_mov_b32_e32 v150, 0x7fc00000
	v_mov_b32_e32 v151, 0x7fc00000
	v_mov_b32_e32 v152, 0x7fc00000
	v_mov_b32_e32 v153, 0x7fc00000
	v_mov_b32_e32 v154, 0x7fc00000
	v_mov_b32_e32 v155, 0x7fc00000
	v_mov_b32_e32 v156, 0x7fc00000
	v_mov_b32_e32 v157, 0x7fc00000
	v_mov_b32_e32 v158, 0x7fc00000
	v_mov_b32_e32 v159, 0x7fc00000
	v_mov_b32_e32 v204, 0
	v_mov_b32_e32 v205, 0
	v_mov_b32_e32 v206, 0
	v_mov_b32_e32 v207, 0
	s_waitcnt lgkmcnt(0)
	v_readfirstlane_b32 s101, v92
	v_readfirstlane_b32 s100, v93
	v_mov_b32_e32 v72, 0
	v_mov_b32_e32 v73, 0
	v_mov_b32_e32 v74, 0
	v_mov_b32_e32 v75, 0
	v_mov_b32_e32 v76, 0
	v_mov_b32_e32 v77, 0
	v_mov_b32_e32 v78, 0
	v_mov_b32_e32 v79, 0
	v_mov_b32_e32 v80, 0
	v_mov_b32_e32 v81, 0
	v_mov_b32_e32 v82, 0
	v_mov_b32_e32 v83, 0
	v_mov_b32_e32 v84, 0
	v_mov_b32_e32 v85, 0
	v_mov_b32_e32 v86, 0
	v_mov_b32_e32 v87, 0
	v_mov_b32_e32 v88, 0
	v_mov_b32_e32 v89, 0
	v_mov_b32_e32 v90, 0
	v_mov_b32_e32 v91, 0
	v_mov_b32_e32 v92, 0
	v_mov_b32_e32 v93, 0
	v_mov_b32_e32 v94, 0
	v_mov_b32_e32 v95, 0
	v_writelane_b32 v255, s50, 30
	v_writelane_b32 v255, s51, 31
	v_writelane_b32 v255, s52, 32
	v_writelane_b32 v255, s53, 33
	v_readfirstlane_b32 s50, v230
	v_readfirstlane_b32 s51, v231
	v_readfirstlane_b32 s52, v228
	v_readfirstlane_b32 s53, v229
	s_nop 3
	v_subrev_u32_e32 v230, s50, v230
	v_subrev_u32_e32 v228, s52, v228
	v_add_u32_e32 v230, v230, v208
	v_add_u32_e32 v228, v228, v208
	v_add_u32_e32 v231, 0x30000, v230
	v_add_u32_e32 v229, 0x400000, v228
	s_add_u32 s50, s50, 0xd660000
	s_addc_u32 s51, s51, 0
	s_add_u32 s52, s52, 0x13600000
	s_addc_u32 s53, s53, 0
	s_mov_b32 s99, 0x7fc00000
	s_add_i32 s12, s19, -1
	s_and_b32 s18, s12, 3
	s_mulk_i32 s18, 0x4800
	s_cmp_lg_u32 s49, 0
	s_cselect_b32 s12, s18, 0
	v_add_u32_e32 v200, s12, v251
	ds_read_b128 v[128:131], v200 offset:16384
	ds_read_b128 v[132:135], v200 offset:20992
	ds_read_b128 v[136:139], v200 offset:25600
	s_cbranch_execnz .LBB0_435
	s_branch .LBB0_434

; __device__ __forceinline__ void attn_unit_a(FLAS unsigned char* lds, const Unit u) {
;     ...
;     if (pend) {
; #pragma unroll
;         for (int d = 0; d < NDB; ++d) o[d] = o[d] * fpend; }
.Lexit_a:
	v_readlane_b32 s50, v255, 30
	v_readlane_b32 s51, v255, 31
	v_readlane_b32 s52, v255, 32
	v_readlane_b32 s53, v255, 33
	s_andn2_b64 vcc, exec, s[0:1]
	s_cbranch_vccnz .LBB0_479
	v_pk_mul_f32 v[62:63], v[62:63], v[226:227] op_sel_hi:[1,0]
	v_pk_mul_f32 v[60:61], v[60:61], v[226:227] op_sel_hi:[1,0]
	v_pk_mul_f32 v[58:59], v[58:59], v[226:227] op_sel_hi:[1,0]
	v_pk_mul_f32 v[56:57], v[56:57], v[226:227] op_sel_hi:[1,0]
	v_pk_mul_f32 v[54:55], v[54:55], v[226:227] op_sel_hi:[1,0]
	v_pk_mul_f32 v[52:53], v[52:53], v[226:227] op_sel_hi:[1,0]
	v_pk_mul_f32 v[50:51], v[50:51], v[226:227] op_sel_hi:[1,0]
	v_pk_mul_f32 v[48:49], v[48:49], v[226:227] op_sel_hi:[1,0]
	v_pk_mul_f32 v[46:47], v[46:47], v[226:227] op_sel_hi:[1,0]
	v_pk_mul_f32 v[44:45], v[44:45], v[226:227] op_sel_hi:[1,0]
	v_pk_mul_f32 v[42:43], v[42:43], v[226:227] op_sel_hi:[1,0]
	v_pk_mul_f32 v[40:41], v[40:41], v[226:227] op_sel_hi:[1,0]
	v_pk_mul_f32 v[38:39], v[38:39], v[226:227] op_sel_hi:[1,0]
	v_pk_mul_f32 v[36:37], v[36:37], v[226:227] op_sel_hi:[1,0]
	v_pk_mul_f32 v[34:35], v[34:35], v[226:227] op_sel_hi:[1,0]
	v_pk_mul_f32 v[32:33], v[32:33], v[226:227] op_sel_hi:[1,0]
	v_pk_mul_f32 v[30:31], v[30:31], v[226:227] op_sel_hi:[1,0]
	v_pk_mul_f32 v[28:29], v[28:29], v[226:227] op_sel_hi:[1,0]
	v_pk_mul_f32 v[26:27], v[26:27], v[226:227] op_sel_hi:[1,0]
	v_pk_mul_f32 v[24:25], v[24:25], v[226:227] op_sel_hi:[1,0]
	v_pk_mul_f32 v[22:23], v[22:23], v[226:227] op_sel_hi:[1,0]
	v_pk_mul_f32 v[20:21], v[20:21], v[226:227] op_sel_hi:[1,0]
	v_pk_mul_f32 v[18:19], v[18:19], v[226:227] op_sel_hi:[1,0]
	v_pk_mul_f32 v[16:17], v[16:17], v[226:227] op_sel_hi:[1,0]
	v_pk_mul_f32 v[14:15], v[14:15], v[226:227] op_sel_hi:[1,0]
	v_pk_mul_f32 v[12:13], v[12:13], v[226:227] op_sel_hi:[1,0]
	v_pk_mul_f32 v[10:11], v[10:11], v[226:227] op_sel_hi:[1,0]
	v_pk_mul_f32 v[8:9], v[8:9], v[226:227] op_sel_hi:[1,0]
	v_pk_mul_f32 v[6:7], v[6:7], v[226:227] op_sel_hi:[1,0]
	v_pk_mul_f32 v[4:5], v[4:5], v[226:227] op_sel_hi:[1,0]
	v_pk_mul_f32 v[2:3], v[2:3], v[226:227] op_sel_hi:[1,0]
	v_pk_mul_f32 v[0:1], v[0:1], v[226:227] op_sel_hi:[1,0]
